# attention loop: static s_setprio 1 for waves 0-3 instead of 4-7 (per-half A/B of the priority raise)
# speedup vs baseline: 1.0002x; 1.0002x over previous
; #define ATT_STAGE_LOAD(SRC, IT) do { _Pragma("unroll") for (int i_ = 0; i_ < 12; ++i_) { const int chunk_ = tid + 512 * i_, rr_ = chunk_ >> 4, ch_ = chunk_ & 15, lv_ = (IT).lq0 - 128 + rr_; \
;         u32x4 val_ = {0u, 0u, 0u, 0u}; if (lv_ >= 0) val_ = *(const u32x4*)((SRC) + ((size_t)lv_ * (IT).d + (IT).res) * 1024 + (IT).hh * 128 + ch_ * 8); stg[i_] = val_; } } while (0)
; #define ATT_QLOAD(IT) do { const size_t qp_ = (size_t)((IT).lq0 + 32 * wave + r) * (IT).d + (IT).res; const bf16* q_ = Q + qp_ * 1024 + (IT).hh * 128 + 8 * h; \
;         _Pragma("unroll") for (int s_ = 0; s_ < 8; ++s_) qf[s_] = *(const bf16x8*)(q_ + 16 * s_); } while (0)
; __device__ __forceinline__ void attn_phase(LAS unsigned char* lds, const bf16* __restrict__ Q, const bf16* __restrict__ Kb, const bf16* __restrict__ Vb, unsigned char* ws, float* PM, int tid, int wave, int lane) {
;     ...
;     AttnItem I = attn_decode(it);
;     u32x4 stg[12]; bf16x8 qf[8];
;     ...
;     ATT_STAGE_LOAD(Kb, I); ATT_QLOAD(I);
.LBB0_572:
	s_or_b64 exec, exec, s[0:1]
	v_add_u32_e32 v1, 0xa00, v186
	v_or_b32_e32 v202, 0x80, v198
	v_lshrrev_b32_e32 v203, 4, v1
	v_add_u32_e32 v4, s3, v202
	v_mov_b32_e32 v5, v80
	v_add_u32_e32 v6, s3, v203
	v_mov_b32_e32 v7, v80
	v_lshlrev_b64 v[4:5], s2, v[4:5]
	v_lshlrev_b64 v[6:7], s2, v[6:7]
	v_lshl_add_u64 v[4:5], v[4:5], 0, s[70:71]
	v_lshl_add_u64 v[6:7], v[6:7], 0, s[70:71]
	v_lshlrev_b64 v[4:5], 11, v[4:5]
	v_lshlrev_b64 v[6:7], 11, v[6:7]
	v_add_u32_e32 v1, 0xe00, v186
	v_lshl_add_u64 v[4:5], v[2:3], 0, v[4:5]
	v_lshl_add_u64 v[6:7], v[2:3], 0, v[6:7]
	v_or_b32_e32 v204, 0xc0, v198
	v_lshrrev_b32_e32 v205, 4, v1
	global_load_dwordx4 v[100:103], v[4:5], off
	global_load_dwordx4 v[104:107], v[6:7], off
	v_add_u32_e32 v4, s3, v204
	v_mov_b32_e32 v5, v80
	v_add_u32_e32 v6, s3, v205
	v_mov_b32_e32 v7, v80
	v_lshlrev_b64 v[4:5], s2, v[4:5]
	v_lshlrev_b64 v[6:7], s2, v[6:7]
	v_lshl_add_u64 v[4:5], v[4:5], 0, s[70:71]
	v_lshl_add_u64 v[6:7], v[6:7], 0, s[70:71]
	v_lshlrev_b64 v[4:5], 11, v[4:5]
	v_lshlrev_b64 v[6:7], 11, v[6:7]
	v_add_u32_e32 v1, 0x1200, v186
	v_lshl_add_u64 v[4:5], v[2:3], 0, v[4:5]
	v_lshl_add_u64 v[6:7], v[2:3], 0, v[6:7]
	v_or_b32_e32 v206, 0x100, v198
	v_lshrrev_b32_e32 v207, 4, v1
	global_load_dwordx4 v[112:115], v[4:5], off
	global_load_dwordx4 v[128:131], v[6:7], off
	v_add_u32_e32 v4, s3, v206
	v_mov_b32_e32 v5, v80
	v_add_u32_e32 v6, s3, v207
	v_mov_b32_e32 v7, v80
	v_lshlrev_b64 v[4:5], s2, v[4:5]
	v_lshlrev_b64 v[6:7], s2, v[6:7]
	v_lshl_add_u64 v[4:5], v[4:5], 0, s[70:71]
	v_lshl_add_u64 v[6:7], v[6:7], 0, s[70:71]
	v_lshlrev_b64 v[4:5], 11, v[4:5]
	v_lshlrev_b64 v[6:7], 11, v[6:7]
	v_add_u32_e32 v1, 0x1600, v186
	v_lshl_add_u64 v[4:5], v[2:3], 0, v[4:5]
	v_lshl_add_u64 v[6:7], v[2:3], 0, v[6:7]
	v_or_b32_e32 v208, 0x140, v198
	v_lshrrev_b32_e32 v209, 4, v1
	global_load_dwordx4 v[148:151], v[4:5], off
	global_load_dwordx4 v[152:155], v[6:7], off
	v_add_u32_e32 v4, s3, v208
	v_mov_b32_e32 v5, v80
	v_add_u32_e32 v6, s3, v209
	v_mov_b32_e32 v7, v80
	v_lshlrev_b64 v[4:5], s2, v[4:5]
	v_lshlrev_b64 v[6:7], s2, v[6:7]
	v_lshl_add_u64 v[4:5], v[4:5], 0, s[70:71]
	v_lshl_add_u64 v[6:7], v[6:7], 0, s[70:71]
	v_lshlrev_b64 v[4:5], 11, v[4:5]
	v_lshlrev_b64 v[6:7], 11, v[6:7]
	s_lshl_b32 s33, s10, 5
	v_lshl_add_u64 v[4:5], v[2:3], 0, v[4:5]
	v_lshl_add_u64 v[2:3], v[2:3], 0, v[6:7]
	s_add_i32 s1, s33, s85
	global_load_dwordx4 v[156:159], v[4:5], off
	global_load_dwordx4 v[160:163], v[2:3], off
	v_or_b32_e32 v2, s1, v185
	v_mov_b32_e32 v3, v80
	v_lshlrev_b64 v[2:3], s2, v[2:3]
	v_lshl_add_u64 v[2:3], v[2:3], 0, s[70:71]
	v_lshlrev_b64 v[2:3], 11, v[2:3]
	v_lshl_add_u64 v[2:3], s[14:15], 0, v[2:3]
	s_lshl_b32 s96, s6, 1
	v_lshl_add_u64 v[2:3], v[2:3], 0, s[96:97]
	v_lshlrev_b32_e32 v6, 4, v187
	v_mov_b32_e32 v7, v80
	v_lshl_add_u64 v[2:3], v[2:3], 0, v[6:7]
	global_load_dwordx4 v[108:111], v[2:3], off
	global_load_dwordx4 v[116:119], v[2:3], off offset:32
	global_load_dwordx4 v[120:123], v[2:3], off offset:64
	global_load_dwordx4 v[124:127], v[2:3], off offset:96
	global_load_dwordx4 v[132:135], v[2:3], off offset:128
	global_load_dwordx4 v[136:139], v[2:3], off offset:160
	global_load_dwordx4 v[140:143], v[2:3], off offset:192
	global_load_dwordx4 v[144:147], v[2:3], off offset:224
	v_lshlrev_b32_e32 v1, 4, v186
	v_and_b32_e32 v1, 0xf0, v1
	v_add_u32_e32 v2, 0, v1
	v_mov_b32_e32 v1, v80
	v_lshl_add_u64 v[190:191], s[4:5], 0, v[0:1]
	v_cmp_gt_u32_e64 s[4:5], 32, v184
	v_lshlrev_b32_e32 v5, 2, v187
	v_or_b32_e32 v14, 1, v5
	v_writelane_b32 v245, s4, 46
	v_lshl_add_u64 v[188:189], s[12:13], 0, v[0:1]
	v_bfe_u32 v0, v186, 2, 2
; #define LAS __attribute__((address_space(3)))
; __device__ __forceinline__ void attn_phase(LAS unsigned char* lds, const bf16* __restrict__ Q, const bf16* __restrict__ Kb, const bf16* __restrict__ Vb, unsigned char* ws, float* PM, int tid, int wave, int lane) {
;     ...
;         const LAS unsigned char* kb = lds + (32 * wave + r) * KROW + h * 16;
;         const int lkw = I.lq0 - 128 + 32 * wave;
; #pragma unroll
;         for (int i = 0; i < 5; ++i) {
; #pragma unroll
;             for (int e = 0; e < 16; ++e) sacc[i][e] = 0.f;
; #pragma unroll
;             for (int s = 0; s < 8; ++s) { const bf16x8 kf = *(const LAS bf16x8*)(kb + (32 * i) * KROW + 32 * s); sacc[i] = __builtin_amdgcn_mfma_f32_32x32x16_bf16(kf, qf[s], sacc[i], 0, 0, 0); }
;         }
; #pragma unroll
;         for (int e = 0; e < 16; ++e) { const int kv = (e & 3) + 8 * (e >> 2) + 4 * h; if (kv < r) sacc[0][e] = -INFINITY; if (kv > r) sacc[4][e] = -INFINITY; }
;     ...
;         const LAS unsigned char* vbase = lds + (32 * wave + 4 * h + ((lane & 15) >> 2)) * VROW + (16 * ((lane >> 4) & 1) + 4 * (lane & 3)) * 2;
	v_writelane_b32 v245, s5, 47
	v_cmp_gt_u32_e64 s[4:5], v5, v185
	v_and_b32_e32 v1, 16, v186
	v_lshlrev_b32_e32 v7, 2, v186
	v_writelane_b32 v245, s4, 48
	s_movk_i32 s0, 0x140
	v_or3_b32 v0, v0, v5, s33
	v_writelane_b32 v245, s5, 49
	v_cmp_lt_u32_e64 s[4:5], v14, v185
	v_or_b32_e32 v14, 2, v5
	v_cmp_lt_u32_e64 s[12:13], v14, v185
	v_cmp_gt_u32_e64 s[14:15], v14, v185
	v_or_b32_e32 v14, 3, v5
	v_cmp_lt_u32_e64 s[16:17], v14, v185
	v_cmp_gt_u32_e64 s[24:25], v14, v185
	v_or_b32_e32 v14, 8, v5
	v_cmp_lt_u32_e64 s[26:27], v14, v185
	v_cmp_gt_u32_e64 s[72:73], v14, v185
	v_or_b32_e32 v14, 9, v5
	v_cmp_lt_u32_e64 s[74:75], v14, v185
	v_cmp_gt_u32_e64 s[78:79], v14, v185
	v_or_b32_e32 v14, 10, v5
	v_cmp_lt_u32_e64 s[28:29], v14, v185
	v_cmp_gt_u32_e64 s[30:31], v14, v185
	v_or_b32_e32 v14, 11, v5
	v_cmp_lt_u32_e64 s[34:35], v14, v185
	v_cmp_gt_u32_e64 s[36:37], v14, v185
	v_or_b32_e32 v14, 16, v5
	v_cmp_lt_u32_e64 s[38:39], v14, v185
	v_cmp_gt_u32_e64 s[40:41], v14, v185
	v_or_b32_e32 v14, 17, v5
	v_cmp_lt_u32_e64 s[42:43], v14, v185
	v_cmp_gt_u32_e64 s[44:45], v14, v185
	v_or_b32_e32 v14, 18, v5
	v_cmp_lt_u32_e64 s[46:47], v14, v185
	v_cmp_gt_u32_e64 s[48:49], v14, v185
	v_or_b32_e32 v14, 19, v5
	v_and_or_b32 v1, v7, 12, v1
	v_cmp_lt_u32_e64 s[50:51], v14, v185
	v_cmp_gt_u32_e64 s[52:53], v14, v185
	v_or_b32_e32 v14, 24, v5
	v_or_b32_e32 v210, s33, v185
	s_movk_i32 s1, 0x110
	v_mul_lo_u32 v0, v0, s0
	v_lshlrev_b32_e32 v1, 1, v1
	v_writelane_b32 v245, s4, 50
	v_cmp_lt_u32_e64 s[54:55], v14, v185
	v_cmp_gt_u32_e64 s[56:57], v14, v185
	v_or_b32_e32 v14, 25, v5
	v_mul_lo_u32 v3, v210, s1
	v_add3_u32 v211, 0, v0, v1
	v_lshrrev_b32_e32 v0, 1, v186
	v_mov_b32_e32 v7, 0x4400
	v_mov_b32_e32 v9, 0x8800
	v_cmp_lt_u32_e64 s[6:7], v5, v185
	v_writelane_b32 v245, s5, 51
	v_cmp_lt_u32_e64 s[58:59], v14, v185
	v_cmp_gt_u32_e64 s[60:61], v14, v185
	v_or_b32_e32 v14, 26, v5
	v_or_b32_e32 v5, 27, v5
	v_mov_b32_e32 v15, 0x5000
	v_mov_b32_e32 v17, 0xa000
	v_lshlrev_b32_e32 v4, 3, v187
	v_add_u32_e32 v3, 0, v3
	v_and_b32_e32 v192, 16, v0
	v_mul_u32_u24_e32 v0, 0x110, v198
	v_mul_u32_u24_e32 v1, 0x110, v199
	v_mad_u32_u24 v7, v198, s1, v7
	v_mul_u32_u24_e32 v8, 0x110, v201
	v_mad_u32_u24 v9, v198, s1, v9
	v_mul_u32_u24_e32 v10, 0x110, v203
	v_mul_u32_u24_e32 v11, 0x110, v205
	v_mul_u32_u24_e32 v12, 0x110, v207
	v_mul_u32_u24_e32 v13, 0x110, v209
	v_cmp_lt_u32_e64 s[62:63], v14, v185
	v_cmp_gt_u32_e64 s[64:65], v14, v185
	v_cmp_lt_u32_e64 s[66:67], v5, v185
	v_cmp_gt_u32_e64 s[68:69], v5, v185
	v_mul_u32_u24_e32 v5, 0x140, v198
	v_mul_u32_u24_e32 v14, 0x140, v199
	v_mad_u32_u24 v15, v198, s0, v15
	v_mul_u32_u24_e32 v16, 0x140, v201
	v_mad_u32_u24 v17, v198, s0, v17
	v_mul_u32_u24_e32 v18, 0x140, v203
	v_mul_u32_u24_e32 v19, 0x140, v205
	v_mul_u32_u24_e32 v20, 0x140, v207
	v_mul_u32_u24_e32 v21, 0x140, v209
	v_readlane_b32 s0, v245, 44
	s_lshl_b32 s3, 1, s2
	v_mov_b32_e32 v193, v80
	v_add_u32_e32 v212, v2, v0
	v_add_u32_e32 v213, v2, v1
	v_add_u32_e32 v214, v2, v8
	v_add_u32_e32 v215, v2, v10
	v_add_u32_e32 v216, v2, v11
	v_add_u32_e32 v217, v2, v7
	v_add_u32_e32 v218, v2, v12
	v_add_u32_e32 v219, v2, v9
	v_add_u32_e32 v220, v2, v13
	v_add_u32_e32 v221, v3, v6
	v_add_u32_e32 v222, v2, v5
	v_add_u32_e32 v223, v2, v14
	v_add_u32_e32 v224, v2, v16
	v_add_u32_e32 v225, v2, v18
	v_add_u32_e32 v226, v2, v19
	v_add_u32_e32 v227, v2, v15
	v_add_u32_e32 v228, v2, v20
	v_add_u32_e32 v229, v2, v17
	v_add_u32_e32 v230, v2, v21
	v_lshlrev_b32_e32 v194, 1, v4
	v_mov_b32_e32 v231, 0xff800000
	s_mov_b32 s96, s70
	s_mov_b32 s2, s0
	v_readlane_b32 s1, v245, 45
	s_cmp_ge_u32 s11, 4
	s_cbranch_scc1 .Latt_prio_done
	s_setprio 1
